# v12 + waves 4-7 run a boosted s_setprio ladder (3,3,2,1) so the younger SIMD partner is not always the one behind
# speedup vs baseline: 1.0002x; 1.0002x over previous
.Lat1_dispatch:
	s_cbranch_scc1 .LBB0_539
	s_cbranch_vccnz .Lat1_skip
	s_and_b64 vcc, exec, s[22:23]
	s_cbranch_vccnz .Lat1_nodma
	s_bitcmp1_b32 s21, 1
	s_cbranch_scc1 .Lat1_young
	s_setprio 3
	v_add_u32_e32 v14, s100, v0
	v_add_u32_e32 v15, s100, v212
	v_add_u32_e32 v176, s100, v213
	v_add_u32_e32 v177, s100, v219
	ds_read_b128 v[144:147], v14 offset:0
	ds_read_b128 v[148:151], v15 offset:0
	ds_read_b128 v[152:155], v176 offset:0
	ds_read_b128 v[156:159], v177 offset:0
	ds_read_b128 v[160:163], v14 offset:8192
	ds_read_b128 v[164:167], v15 offset:8192
	ds_read_b128 v[168:171], v176 offset:8192
	ds_read_b128 v[172:175], v177 offset:8192
	ds_read_b128 v[2:5], v14 offset:16384
	ds_read_b128 v[6:9], v15 offset:16384
	ds_read_b128 v[10:13], v176 offset:16384
	ds_read_b128 v[238:241], v177 offset:16384
	s_waitcnt lgkmcnt(8)
	v_mfma_f32_32x32x16_bf16 v[80:95], v[144:147], v[132:135], 0
	v_mfma_f32_32x32x16_bf16 v[80:95], v[148:151], v[128:131], v[80:95]
	v_mfma_f32_32x32x16_bf16 v[80:95], v[152:155], v[124:127], v[80:95]
	v_mfma_f32_32x32x16_bf16 v[80:95], v[156:159], v[120:123], v[80:95]
	ds_read_b128 v[144:147], v14 offset:4096
	ds_read_b128 v[148:151], v15 offset:4096
	ds_read_b128 v[152:155], v176 offset:4096
	ds_read_b128 v[156:159], v177 offset:4096
	s_waitcnt lgkmcnt(8)
	v_mfma_f32_32x32x16_bf16 v[80:95], v[160:163], v[116:119], v[80:95]
	v_mfma_f32_32x32x16_bf16 v[80:95], v[164:167], v[112:115], v[80:95]
	v_mfma_f32_32x32x16_bf16 v[80:95], v[168:171], v[108:111], v[80:95]
	v_mfma_f32_32x32x16_bf16 v[80:95], v[172:175], v[104:107], v[80:95]
	ds_read_b128 v[160:163], v14 offset:12288
	ds_read_b128 v[164:167], v15 offset:12288
	ds_read_b128 v[168:171], v176 offset:12288
	ds_read_b128 v[172:175], v177 offset:12288
	s_waitcnt lgkmcnt(8)
	v_mfma_f32_32x32x16_bf16 v[80:95], v[2:5], v[100:103], v[80:95]
	v_mfma_f32_32x32x16_bf16 v[80:95], v[6:9], v[140:143], v[80:95]
	v_mfma_f32_32x32x16_bf16 v[80:95], v[10:13], v[96:99], v[80:95]
	v_mfma_f32_32x32x16_bf16 v[80:95], v[238:241], v[136:139], v[80:95]
	s_setprio 2
	ds_read_b128 v[2:5], v14 offset:20480
	ds_read_b128 v[6:9], v15 offset:20480
	ds_read_b128 v[10:13], v176 offset:20480
	ds_read_b128 v[238:241], v177 offset:20480
	s_waitcnt lgkmcnt(8)
	v_mfma_f32_32x32x16_bf16 v[184:199], v[144:147], v[132:135], 0
	v_mfma_f32_32x32x16_bf16 v[184:199], v[148:151], v[128:131], v[184:199]
	v_mfma_f32_32x32x16_bf16 v[184:199], v[152:155], v[124:127], v[184:199]
	v_mfma_f32_32x32x16_bf16 v[184:199], v[156:159], v[120:123], v[184:199]
	ds_read_b128 v[144:147], v14 offset:24576
	ds_read_b128 v[148:151], v14 offset:28672
	ds_read_b128 v[152:155], v14 offset:32768
	ds_read_b128 v[156:159], v14 offset:36864
	s_waitcnt lgkmcnt(8)
	v_mfma_f32_32x32x16_bf16 v[184:199], v[160:163], v[116:119], v[184:199]
	v_med3_f32 v80, v80, s4, v236
	v_exp_f32_e32 v80, v80
	v_med3_f32 v81, v81, s4, v236
	v_exp_f32_e32 v81, v81
	v_mfma_f32_32x32x16_bf16 v[184:199], v[164:167], v[112:115], v[184:199]
	v_med3_f32 v82, v82, s4, v236
	v_exp_f32_e32 v82, v82
	v_med3_f32 v83, v83, s4, v236
	v_exp_f32_e32 v83, v83
	v_mfma_f32_32x32x16_bf16 v[184:199], v[168:171], v[108:111], v[184:199]
	v_med3_f32 v84, v84, s4, v236
	v_exp_f32_e32 v84, v84
	v_med3_f32 v85, v85, s4, v236
	v_exp_f32_e32 v85, v85
	v_mfma_f32_32x32x16_bf16 v[184:199], v[172:175], v[104:107], v[184:199]
	v_med3_f32 v86, v86, s4, v236
	v_exp_f32_e32 v86, v86
	v_med3_f32 v87, v87, s4, v236
	v_exp_f32_e32 v87, v87
	ds_read_b128 v[160:163], v15 offset:24576
	ds_read_b128 v[164:167], v15 offset:28672
	ds_read_b128 v[168:171], v15 offset:32768
	ds_read_b128 v[172:175], v15 offset:36864
	s_waitcnt lgkmcnt(8)
	v_mfma_f32_32x32x16_bf16 v[184:199], v[2:5], v[100:103], v[184:199]
	v_med3_f32 v88, v88, s4, v236
	v_exp_f32_e32 v88, v88
	v_med3_f32 v89, v89, s4, v236
	v_exp_f32_e32 v89, v89
	v_add_f32_e32 v200, v80, v81
	v_add_f32_e32 v200, v200, v82
	v_mfma_f32_32x32x16_bf16 v[184:199], v[6:9], v[140:143], v[184:199]
	v_med3_f32 v90, v90, s4, v236
	v_exp_f32_e32 v90, v90
	v_med3_f32 v91, v91, s4, v236
	v_exp_f32_e32 v91, v91
	v_add_f32_e32 v200, v200, v83
	v_add_f32_e32 v200, v200, v84
	v_mfma_f32_32x32x16_bf16 v[184:199], v[10:13], v[96:99], v[184:199]
	v_med3_f32 v92, v92, s4, v236
	v_exp_f32_e32 v92, v92
	v_med3_f32 v93, v93, s4, v236
	v_exp_f32_e32 v93, v93
	v_add_f32_e32 v200, v200, v85
	v_add_f32_e32 v200, v200, v86
	v_mfma_f32_32x32x16_bf16 v[184:199], v[238:241], v[136:139], v[184:199]
	v_med3_f32 v94, v94, s4, v236
	v_exp_f32_e32 v94, v94
	v_med3_f32 v95, v95, s4, v236
	v_exp_f32_e32 v95, v95
	v_add_f32_e32 v200, v200, v87
	s_setprio 1
	ds_read_b128 v[2:5], v176 offset:24576
	ds_read_b128 v[6:9], v176 offset:28672
	ds_read_b128 v[10:13], v176 offset:32768
	ds_read_b128 v[238:241], v176 offset:36864
	v_cvt_pk_bf16_f32 v80, v80, v81
	v_cvt_pk_bf16_f32 v81, v82, v83
	v_cvt_pk_bf16_f32 v82, v84, v85
	v_cvt_pk_bf16_f32 v83, v86, v87
	v_add_f32_e32 v200, v200, v88
	v_add_f32_e32 v200, v200, v89
	s_waitcnt lgkmcnt(8)
	v_mfma_f32_32x32x16_bf16 v[64:79], v[80:83], v[144:147], v[64:79]
	v_med3_f32 v184, v184, s4, v236
	v_exp_f32_e32 v184, v184
	v_med3_f32 v185, v185, s4, v236
	v_exp_f32_e32 v185, v185
	v_add_f32_e32 v200, v200, v90
	v_add_f32_e32 v200, v200, v91
	v_mfma_f32_32x32x16_bf16 v[48:63], v[80:83], v[148:151], v[48:63]
	v_med3_f32 v186, v186, s4, v236
	v_exp_f32_e32 v186, v186
	v_med3_f32 v187, v187, s4, v236
	v_exp_f32_e32 v187, v187
	v_add_f32_e32 v200, v200, v92
	v_add_f32_e32 v200, v200, v93
	v_mfma_f32_32x32x16_bf16 v[32:47], v[80:83], v[152:155], v[32:47]
	v_med3_f32 v188, v188, s4, v236
	v_exp_f32_e32 v188, v188
	v_med3_f32 v189, v189, s4, v236
	v_exp_f32_e32 v189, v189
	v_add_f32_e32 v200, v200, v94
	v_add_f32_e32 v200, v200, v95
	v_mfma_f32_32x32x16_bf16 v[16:31], v[80:83], v[156:159], v[16:31]
	v_med3_f32 v190, v190, s4, v236
	v_exp_f32_e32 v190, v190
	v_med3_f32 v191, v191, s4, v236
	v_exp_f32_e32 v191, v191
	v_cvt_pk_bf16_f32 v84, v88, v89
	v_cvt_pk_bf16_f32 v85, v90, v91
	v_cvt_pk_bf16_f32 v86, v92, v93
	v_cvt_pk_bf16_f32 v87, v94, v95
	ds_read_b128 v[144:147], v177 offset:24576
	ds_read_b128 v[148:151], v177 offset:28672
	ds_read_b128 v[152:155], v177 offset:32768
	ds_read_b128 v[156:159], v177 offset:36864
	s_waitcnt lgkmcnt(8)
	v_mfma_f32_32x32x16_bf16 v[64:79], v[84:87], v[160:163], v[64:79]
	v_med3_f32 v192, v192, s4, v236
	v_exp_f32_e32 v192, v192
	v_med3_f32 v193, v193, s4, v236
	v_exp_f32_e32 v193, v193
	v_add_f32_e32 v201, v184, v185
	v_add_f32_e32 v201, v201, v186
	v_mfma_f32_32x32x16_bf16 v[48:63], v[84:87], v[164:167], v[48:63]
	v_med3_f32 v194, v194, s4, v236
	v_exp_f32_e32 v194, v194
	v_med3_f32 v195, v195, s4, v236
	v_exp_f32_e32 v195, v195
	v_add_f32_e32 v201, v201, v187
	v_add_f32_e32 v201, v201, v188
	v_mfma_f32_32x32x16_bf16 v[32:47], v[84:87], v[168:171], v[32:47]
	v_med3_f32 v196, v196, s4, v236
	v_exp_f32_e32 v196, v196
	v_med3_f32 v197, v197, s4, v236
	v_exp_f32_e32 v197, v197
	v_add_f32_e32 v201, v201, v189
	v_mfma_f32_32x32x16_bf16 v[16:31], v[84:87], v[172:175], v[16:31]
	v_med3_f32 v198, v198, s4, v236
	v_exp_f32_e32 v198, v198
	v_med3_f32 v199, v199, s4, v236
	v_exp_f32_e32 v199, v199
	v_add_f32_e32 v201, v201, v190
	v_cvt_pk_bf16_f32 v184, v184, v185
	v_cvt_pk_bf16_f32 v185, v186, v187
	v_cvt_pk_bf16_f32 v186, v188, v189
	v_cvt_pk_bf16_f32 v187, v190, v191
	v_add_f32_e32 v201, v201, v191
	s_setprio 0
	s_waitcnt lgkmcnt(4)
	v_mfma_f32_32x32x16_bf16 v[64:79], v[184:187], v[2:5], v[64:79]
	v_mad_u64_u32 v[202:203], s[10:11], s86, v228, v[180:181]
	s_mul_i32 s10, s7, 0xa000
	s_add_i32 s10, s9, s10
	s_mov_b32 m0, s10
	v_lshl_add_u64 v[204:205], v[202:203], 0, s[94:95]
	global_load_lds_dwordx4 v[202:203], off
	v_add_f32_e32 v201, v201, v192
	v_add_f32_e32 v201, v201, v193
	v_add_f32_e32 v201, v201, v194
	v_mfma_f32_32x32x16_bf16 v[48:63], v[184:187], v[6:9], v[48:63]
	s_add_i32 m0, s10, 0x2000
	v_lshl_add_u64 v[202:203], v[202:203], 0, s[96:97]
	global_load_lds_dwordx4 v[204:205], off
	v_add_f32_e32 v201, v201, v195
	v_add_f32_e32 v201, v201, v196
	v_add_f32_e32 v201, v201, v197
	v_mfma_f32_32x32x16_bf16 v[32:47], v[184:187], v[10:13], v[32:47]
	s_add_i32 m0, s10, 0x4000
	s_nop 0
	global_load_lds_dwordx4 v[202:203], off
	v_lshl_add_u64 v[202:203], s[86:87], 1, v[182:183]
	s_add_i32 m0, s10, 0x6000
	v_add_f32_e32 v201, v201, v198
	v_add_f32_e32 v201, v201, v199
	v_cvt_pk_bf16_f32 v188, v192, v193
	v_cvt_pk_bf16_f32 v189, v194, v195
	v_cvt_pk_bf16_f32 v190, v196, v197
	v_cvt_pk_bf16_f32 v191, v198, v199
	v_mfma_f32_32x32x16_bf16 v[16:31], v[184:187], v[238:241], v[16:31]
	global_load_lds_dwordx4 v[202:203], off
	v_lshl_add_u64 v[202:203], v[202:203], 0, s[92:93]
	s_add_i32 m0, s10, 0x8000
	v_add_f32_e32 v200, v200, v201
	v_add_f32_e32 v218, v218, v200
	s_waitcnt lgkmcnt(0)
	v_mfma_f32_32x32x16_bf16 v[64:79], v[188:191], v[144:147], v[64:79]
	global_load_lds_dwordx4 v[202:203], off
	v_mfma_f32_32x32x16_bf16 v[48:63], v[188:191], v[148:151], v[48:63]
	v_mfma_f32_32x32x16_bf16 v[32:47], v[188:191], v[152:155], v[32:47]
	v_mfma_f32_32x32x16_bf16 v[16:31], v[188:191], v[156:159], v[16:31]
	s_waitcnt vmcnt(5) lgkmcnt(0)
	s_branch .LBB0_530
.Lat1_young:
	s_setprio 3
	v_add_u32_e32 v14, s100, v0
	v_add_u32_e32 v15, s100, v212
	v_add_u32_e32 v176, s100, v213
	v_add_u32_e32 v177, s100, v219
	ds_read_b128 v[144:147], v14 offset:0
	ds_read_b128 v[148:151], v15 offset:0
	ds_read_b128 v[152:155], v176 offset:0
	ds_read_b128 v[156:159], v177 offset:0
	ds_read_b128 v[160:163], v14 offset:8192
	ds_read_b128 v[164:167], v15 offset:8192
	ds_read_b128 v[168:171], v176 offset:8192
	ds_read_b128 v[172:175], v177 offset:8192
	ds_read_b128 v[2:5], v14 offset:16384
	ds_read_b128 v[6:9], v15 offset:16384
	ds_read_b128 v[10:13], v176 offset:16384
	ds_read_b128 v[238:241], v177 offset:16384
	s_waitcnt lgkmcnt(8)
	v_mfma_f32_32x32x16_bf16 v[80:95], v[144:147], v[132:135], 0
	v_mfma_f32_32x32x16_bf16 v[80:95], v[148:151], v[128:131], v[80:95]
	v_mfma_f32_32x32x16_bf16 v[80:95], v[152:155], v[124:127], v[80:95]
	v_mfma_f32_32x32x16_bf16 v[80:95], v[156:159], v[120:123], v[80:95]
	ds_read_b128 v[144:147], v14 offset:4096
	ds_read_b128 v[148:151], v15 offset:4096
	ds_read_b128 v[152:155], v176 offset:4096
	ds_read_b128 v[156:159], v177 offset:4096
	s_waitcnt lgkmcnt(8)
	v_mfma_f32_32x32x16_bf16 v[80:95], v[160:163], v[116:119], v[80:95]
	v_mfma_f32_32x32x16_bf16 v[80:95], v[164:167], v[112:115], v[80:95]
	v_mfma_f32_32x32x16_bf16 v[80:95], v[168:171], v[108:111], v[80:95]
	v_mfma_f32_32x32x16_bf16 v[80:95], v[172:175], v[104:107], v[80:95]
	ds_read_b128 v[160:163], v14 offset:12288
	ds_read_b128 v[164:167], v15 offset:12288
	ds_read_b128 v[168:171], v176 offset:12288
	ds_read_b128 v[172:175], v177 offset:12288
	s_waitcnt lgkmcnt(8)
	v_mfma_f32_32x32x16_bf16 v[80:95], v[2:5], v[100:103], v[80:95]
	v_mfma_f32_32x32x16_bf16 v[80:95], v[6:9], v[140:143], v[80:95]
	v_mfma_f32_32x32x16_bf16 v[80:95], v[10:13], v[96:99], v[80:95]
	v_mfma_f32_32x32x16_bf16 v[80:95], v[238:241], v[136:139], v[80:95]
	s_setprio 3
	ds_read_b128 v[2:5], v14 offset:20480
	ds_read_b128 v[6:9], v15 offset:20480
	ds_read_b128 v[10:13], v176 offset:20480
	ds_read_b128 v[238:241], v177 offset:20480
	s_waitcnt lgkmcnt(8)
	v_mfma_f32_32x32x16_bf16 v[184:199], v[144:147], v[132:135], 0
	v_mfma_f32_32x32x16_bf16 v[184:199], v[148:151], v[128:131], v[184:199]
	v_mfma_f32_32x32x16_bf16 v[184:199], v[152:155], v[124:127], v[184:199]
	v_mfma_f32_32x32x16_bf16 v[184:199], v[156:159], v[120:123], v[184:199]
	ds_read_b128 v[144:147], v14 offset:24576
	ds_read_b128 v[148:151], v14 offset:28672
	ds_read_b128 v[152:155], v14 offset:32768
	ds_read_b128 v[156:159], v14 offset:36864
	s_waitcnt lgkmcnt(8)
	v_mfma_f32_32x32x16_bf16 v[184:199], v[160:163], v[116:119], v[184:199]
	v_med3_f32 v80, v80, s4, v236
	v_exp_f32_e32 v80, v80
	v_med3_f32 v81, v81, s4, v236
	v_exp_f32_e32 v81, v81
	v_mfma_f32_32x32x16_bf16 v[184:199], v[164:167], v[112:115], v[184:199]
	v_med3_f32 v82, v82, s4, v236
	v_exp_f32_e32 v82, v82
	v_med3_f32 v83, v83, s4, v236
	v_exp_f32_e32 v83, v83
	v_mfma_f32_32x32x16_bf16 v[184:199], v[168:171], v[108:111], v[184:199]
	v_med3_f32 v84, v84, s4, v236
	v_exp_f32_e32 v84, v84
	v_med3_f32 v85, v85, s4, v236
	v_exp_f32_e32 v85, v85
	v_mfma_f32_32x32x16_bf16 v[184:199], v[172:175], v[104:107], v[184:199]
	v_med3_f32 v86, v86, s4, v236
	v_exp_f32_e32 v86, v86
	v_med3_f32 v87, v87, s4, v236
	v_exp_f32_e32 v87, v87
	ds_read_b128 v[160:163], v15 offset:24576
	ds_read_b128 v[164:167], v15 offset:28672
	ds_read_b128 v[168:171], v15 offset:32768
	ds_read_b128 v[172:175], v15 offset:36864
	s_waitcnt lgkmcnt(8)
	v_mfma_f32_32x32x16_bf16 v[184:199], v[2:5], v[100:103], v[184:199]
	v_med3_f32 v88, v88, s4, v236
	v_exp_f32_e32 v88, v88
	v_med3_f32 v89, v89, s4, v236
	v_exp_f32_e32 v89, v89
	v_add_f32_e32 v200, v80, v81
	v_add_f32_e32 v200, v200, v82
	v_mfma_f32_32x32x16_bf16 v[184:199], v[6:9], v[140:143], v[184:199]
	v_med3_f32 v90, v90, s4, v236
	v_exp_f32_e32 v90, v90
	v_med3_f32 v91, v91, s4, v236
	v_exp_f32_e32 v91, v91
	v_add_f32_e32 v200, v200, v83
	v_add_f32_e32 v200, v200, v84
	v_mfma_f32_32x32x16_bf16 v[184:199], v[10:13], v[96:99], v[184:199]
	v_med3_f32 v92, v92, s4, v236
	v_exp_f32_e32 v92, v92
	v_med3_f32 v93, v93, s4, v236
	v_exp_f32_e32 v93, v93
	v_add_f32_e32 v200, v200, v85
	v_add_f32_e32 v200, v200, v86
	v_mfma_f32_32x32x16_bf16 v[184:199], v[238:241], v[136:139], v[184:199]
	v_med3_f32 v94, v94, s4, v236
	v_exp_f32_e32 v94, v94
	v_med3_f32 v95, v95, s4, v236
	v_exp_f32_e32 v95, v95
	v_add_f32_e32 v200, v200, v87
	s_setprio 2
	ds_read_b128 v[2:5], v176 offset:24576
	ds_read_b128 v[6:9], v176 offset:28672
	ds_read_b128 v[10:13], v176 offset:32768
	ds_read_b128 v[238:241], v176 offset:36864
	v_cvt_pk_bf16_f32 v80, v80, v81
	v_cvt_pk_bf16_f32 v81, v82, v83
	v_cvt_pk_bf16_f32 v82, v84, v85
	v_cvt_pk_bf16_f32 v83, v86, v87
	v_add_f32_e32 v200, v200, v88
	v_add_f32_e32 v200, v200, v89
	s_waitcnt lgkmcnt(8)
	v_mfma_f32_32x32x16_bf16 v[64:79], v[80:83], v[144:147], v[64:79]
	v_med3_f32 v184, v184, s4, v236
	v_exp_f32_e32 v184, v184
	v_med3_f32 v185, v185, s4, v236
	v_exp_f32_e32 v185, v185
	v_add_f32_e32 v200, v200, v90
	v_add_f32_e32 v200, v200, v91
	v_mfma_f32_32x32x16_bf16 v[48:63], v[80:83], v[148:151], v[48:63]
	v_med3_f32 v186, v186, s4, v236
	v_exp_f32_e32 v186, v186
	v_med3_f32 v187, v187, s4, v236
	v_exp_f32_e32 v187, v187
	v_add_f32_e32 v200, v200, v92
	v_add_f32_e32 v200, v200, v93
	v_mfma_f32_32x32x16_bf16 v[32:47], v[80:83], v[152:155], v[32:47]
	v_med3_f32 v188, v188, s4, v236
	v_exp_f32_e32 v188, v188
	v_med3_f32 v189, v189, s4, v236
	v_exp_f32_e32 v189, v189
	v_add_f32_e32 v200, v200, v94
	v_add_f32_e32 v200, v200, v95
	v_mfma_f32_32x32x16_bf16 v[16:31], v[80:83], v[156:159], v[16:31]
	v_med3_f32 v190, v190, s4, v236
	v_exp_f32_e32 v190, v190
	v_med3_f32 v191, v191, s4, v236
	v_exp_f32_e32 v191, v191
	v_cvt_pk_bf16_f32 v84, v88, v89
	v_cvt_pk_bf16_f32 v85, v90, v91
	v_cvt_pk_bf16_f32 v86, v92, v93
	v_cvt_pk_bf16_f32 v87, v94, v95
	ds_read_b128 v[144:147], v177 offset:24576
	ds_read_b128 v[148:151], v177 offset:28672
	ds_read_b128 v[152:155], v177 offset:32768
	ds_read_b128 v[156:159], v177 offset:36864
	s_waitcnt lgkmcnt(8)
	v_mfma_f32_32x32x16_bf16 v[64:79], v[84:87], v[160:163], v[64:79]
	v_med3_f32 v192, v192, s4, v236
	v_exp_f32_e32 v192, v192
	v_med3_f32 v193, v193, s4, v236
	v_exp_f32_e32 v193, v193
	v_add_f32_e32 v201, v184, v185
	v_add_f32_e32 v201, v201, v186
	v_mfma_f32_32x32x16_bf16 v[48:63], v[84:87], v[164:167], v[48:63]
	v_med3_f32 v194, v194, s4, v236
	v_exp_f32_e32 v194, v194
	v_med3_f32 v195, v195, s4, v236
	v_exp_f32_e32 v195, v195
	v_add_f32_e32 v201, v201, v187
	v_add_f32_e32 v201, v201, v188
	v_mfma_f32_32x32x16_bf16 v[32:47], v[84:87], v[168:171], v[32:47]
	v_med3_f32 v196, v196, s4, v236
	v_exp_f32_e32 v196, v196
	v_med3_f32 v197, v197, s4, v236
	v_exp_f32_e32 v197, v197
	v_add_f32_e32 v201, v201, v189
	v_mfma_f32_32x32x16_bf16 v[16:31], v[84:87], v[172:175], v[16:31]
	v_med3_f32 v198, v198, s4, v236
	v_exp_f32_e32 v198, v198
	v_med3_f32 v199, v199, s4, v236
	v_exp_f32_e32 v199, v199
	v_add_f32_e32 v201, v201, v190
	v_cvt_pk_bf16_f32 v184, v184, v185
	v_cvt_pk_bf16_f32 v185, v186, v187
	v_cvt_pk_bf16_f32 v186, v188, v189
	v_cvt_pk_bf16_f32 v187, v190, v191
	v_add_f32_e32 v201, v201, v191
	s_setprio 1
	s_waitcnt lgkmcnt(4)
	v_mfma_f32_32x32x16_bf16 v[64:79], v[184:187], v[2:5], v[64:79]
	v_mad_u64_u32 v[202:203], s[10:11], s86, v228, v[180:181]
	s_mul_i32 s10, s7, 0xa000
	s_add_i32 s10, s9, s10
	s_mov_b32 m0, s10
	v_lshl_add_u64 v[204:205], v[202:203], 0, s[94:95]
	global_load_lds_dwordx4 v[202:203], off
	v_add_f32_e32 v201, v201, v192
	v_add_f32_e32 v201, v201, v193
	v_add_f32_e32 v201, v201, v194
	v_mfma_f32_32x32x16_bf16 v[48:63], v[184:187], v[6:9], v[48:63]
	s_add_i32 m0, s10, 0x2000
	v_lshl_add_u64 v[202:203], v[202:203], 0, s[96:97]
	global_load_lds_dwordx4 v[204:205], off
	v_add_f32_e32 v201, v201, v195
	v_add_f32_e32 v201, v201, v196
	v_add_f32_e32 v201, v201, v197
	v_mfma_f32_32x32x16_bf16 v[32:47], v[184:187], v[10:13], v[32:47]
	s_add_i32 m0, s10, 0x4000
	s_nop 0
	global_load_lds_dwordx4 v[202:203], off
	v_lshl_add_u64 v[202:203], s[86:87], 1, v[182:183]
	s_add_i32 m0, s10, 0x6000
	v_add_f32_e32 v201, v201, v198
	v_add_f32_e32 v201, v201, v199
	v_cvt_pk_bf16_f32 v188, v192, v193
	v_cvt_pk_bf16_f32 v189, v194, v195
	v_cvt_pk_bf16_f32 v190, v196, v197
	v_cvt_pk_bf16_f32 v191, v198, v199
	v_mfma_f32_32x32x16_bf16 v[16:31], v[184:187], v[238:241], v[16:31]
	global_load_lds_dwordx4 v[202:203], off
	v_lshl_add_u64 v[202:203], v[202:203], 0, s[92:93]
	s_add_i32 m0, s10, 0x8000
	v_add_f32_e32 v200, v200, v201
	v_add_f32_e32 v218, v218, v200
	s_waitcnt lgkmcnt(0)
	v_mfma_f32_32x32x16_bf16 v[64:79], v[188:191], v[144:147], v[64:79]
	global_load_lds_dwordx4 v[202:203], off
	v_mfma_f32_32x32x16_bf16 v[48:63], v[188:191], v[148:151], v[48:63]
	v_mfma_f32_32x32x16_bf16 v[32:47], v[188:191], v[152:155], v[32:47]
	v_mfma_f32_32x32x16_bf16 v[16:31], v[188:191], v[156:159], v[16:31]
	s_setprio 0
	s_waitcnt vmcnt(5) lgkmcnt(0)
	s_branch .LBB0_530

.Lat2_dispatch:
	s_cbranch_scc1 .LBB0_583
	s_cbranch_vccnz .Lat2_skip
	s_and_b64 vcc, exec, s[22:23]
	s_cbranch_vccnz .Lat2_nodma
	s_bitcmp1_b32 s9, 1
	s_cbranch_scc1 .Lat2_young
	s_setprio 3
	v_add_u32_e32 v198, s100, v218
	v_add_u32_e32 v199, s100, v219
	v_add_u32_e32 v200, s100, v209
	v_add_u32_e32 v201, s100, v208
	ds_read_b128 v[130:133], v198 offset:0
	ds_read_b128 v[134:137], v199 offset:0
	ds_read_b128 v[138:141], v200 offset:0
	ds_read_b128 v[142:145], v201 offset:0
	ds_read_b128 v[146:149], v198 offset:8192
	ds_read_b128 v[150:153], v199 offset:8192
	ds_read_b128 v[154:157], v200 offset:8192
	ds_read_b128 v[158:161], v201 offset:8192
	ds_read_b128 v[162:165], v198 offset:16384
	ds_read_b128 v[166:169], v199 offset:16384
	ds_read_b128 v[170:173], v200 offset:16384
	ds_read_b128 v[176:179], v201 offset:16384
	s_waitcnt lgkmcnt(8)
	v_mfma_f32_32x32x16_bf16 v[66:81], v[130:133], v[118:121], 0
	v_mfma_f32_32x32x16_bf16 v[66:81], v[134:137], v[114:117], v[66:81]
	v_mfma_f32_32x32x16_bf16 v[66:81], v[138:141], v[110:113], v[66:81]
	v_mfma_f32_32x32x16_bf16 v[66:81], v[142:145], v[106:109], v[66:81]
	ds_read_b128 v[130:133], v198 offset:4096
	ds_read_b128 v[134:137], v199 offset:4096
	ds_read_b128 v[138:141], v200 offset:4096
	ds_read_b128 v[142:145], v201 offset:4096
	s_waitcnt lgkmcnt(8)
	v_mfma_f32_32x32x16_bf16 v[66:81], v[146:149], v[102:105], v[66:81]
	v_mfma_f32_32x32x16_bf16 v[66:81], v[150:153], v[98:101], v[66:81]
	v_mfma_f32_32x32x16_bf16 v[66:81], v[154:157], v[94:97], v[66:81]
	v_mfma_f32_32x32x16_bf16 v[66:81], v[158:161], v[90:93], v[66:81]
	ds_read_b128 v[146:149], v198 offset:12288
	ds_read_b128 v[150:153], v199 offset:12288
	ds_read_b128 v[154:157], v200 offset:12288
	ds_read_b128 v[158:161], v201 offset:12288
	s_waitcnt lgkmcnt(8)
	v_mfma_f32_32x32x16_bf16 v[66:81], v[162:165], v[86:89], v[66:81]
	v_mfma_f32_32x32x16_bf16 v[66:81], v[166:169], v[126:129], v[66:81]
	v_mfma_f32_32x32x16_bf16 v[66:81], v[170:173], v[82:85], v[66:81]
	v_mfma_f32_32x32x16_bf16 v[66:81], v[176:179], v[122:125], v[66:81]
	s_setprio 2
	ds_read_b128 v[162:165], v198 offset:20480
	ds_read_b128 v[166:169], v199 offset:20480
	ds_read_b128 v[170:173], v200 offset:20480
	ds_read_b128 v[176:179], v201 offset:20480
	s_waitcnt lgkmcnt(8)
	v_mfma_f32_32x32x16_bf16 v[182:197], v[130:133], v[118:121], 0
	v_mfma_f32_32x32x16_bf16 v[182:197], v[134:137], v[114:117], v[182:197]
	v_mfma_f32_32x32x16_bf16 v[182:197], v[138:141], v[110:113], v[182:197]
	v_mfma_f32_32x32x16_bf16 v[182:197], v[142:145], v[106:109], v[182:197]
	ds_read_b128 v[130:133], v198 offset:24576
	ds_read_b128 v[134:137], v198 offset:28672
	ds_read_b128 v[138:141], v198 offset:32768
	ds_read_b128 v[142:145], v198 offset:36864
	s_waitcnt lgkmcnt(8)
	v_mfma_f32_32x32x16_bf16 v[182:197], v[146:149], v[102:105], v[182:197]
	v_med3_f32 v66, v66, s4, v236
	v_exp_f32_e32 v66, v66
	v_med3_f32 v67, v67, s4, v236
	v_exp_f32_e32 v67, v67
	v_mfma_f32_32x32x16_bf16 v[182:197], v[150:153], v[98:101], v[182:197]
	v_med3_f32 v68, v68, s4, v236
	v_exp_f32_e32 v68, v68
	v_med3_f32 v69, v69, s4, v236
	v_exp_f32_e32 v69, v69
	v_mfma_f32_32x32x16_bf16 v[182:197], v[154:157], v[94:97], v[182:197]
	v_med3_f32 v70, v70, s4, v236
	v_exp_f32_e32 v70, v70
	v_med3_f32 v71, v71, s4, v236
	v_exp_f32_e32 v71, v71
	v_mfma_f32_32x32x16_bf16 v[182:197], v[158:161], v[90:93], v[182:197]
	v_med3_f32 v72, v72, s4, v236
	v_exp_f32_e32 v72, v72
	v_med3_f32 v73, v73, s4, v236
	v_exp_f32_e32 v73, v73
	ds_read_b128 v[146:149], v199 offset:24576
	ds_read_b128 v[150:153], v199 offset:28672
	ds_read_b128 v[154:157], v199 offset:32768
	ds_read_b128 v[158:161], v199 offset:36864
	s_waitcnt lgkmcnt(8)
	v_mfma_f32_32x32x16_bf16 v[182:197], v[162:165], v[86:89], v[182:197]
	v_med3_f32 v74, v74, s4, v236
	v_exp_f32_e32 v74, v74
	v_med3_f32 v75, v75, s4, v236
	v_exp_f32_e32 v75, v75
	v_add_f32_e32 v202, v66, v67
	v_add_f32_e32 v202, v202, v68
	v_mfma_f32_32x32x16_bf16 v[182:197], v[166:169], v[126:129], v[182:197]
	v_med3_f32 v76, v76, s4, v236
	v_exp_f32_e32 v76, v76
	v_med3_f32 v77, v77, s4, v236
	v_exp_f32_e32 v77, v77
	v_add_f32_e32 v202, v202, v69
	v_add_f32_e32 v202, v202, v70
	v_mfma_f32_32x32x16_bf16 v[182:197], v[170:173], v[82:85], v[182:197]
	v_med3_f32 v78, v78, s4, v236
	v_exp_f32_e32 v78, v78
	v_med3_f32 v79, v79, s4, v236
	v_exp_f32_e32 v79, v79
	v_add_f32_e32 v202, v202, v71
	v_add_f32_e32 v202, v202, v72
	v_mfma_f32_32x32x16_bf16 v[182:197], v[176:179], v[122:125], v[182:197]
	v_med3_f32 v80, v80, s4, v236
	v_exp_f32_e32 v80, v80
	v_med3_f32 v81, v81, s4, v236
	v_exp_f32_e32 v81, v81
	v_add_f32_e32 v202, v202, v73
	s_setprio 1
	ds_read_b128 v[162:165], v200 offset:24576
	ds_read_b128 v[166:169], v200 offset:28672
	ds_read_b128 v[170:173], v200 offset:32768
	ds_read_b128 v[176:179], v200 offset:36864
	v_cvt_pk_bf16_f32 v66, v66, v67
	v_cvt_pk_bf16_f32 v67, v68, v69
	v_cvt_pk_bf16_f32 v68, v70, v71
	v_cvt_pk_bf16_f32 v69, v72, v73
	v_add_f32_e32 v202, v202, v74
	v_add_f32_e32 v202, v202, v75
	s_waitcnt lgkmcnt(8)
	v_mfma_f32_32x32x16_bf16 v[50:65], v[66:69], v[130:133], v[50:65]
	v_med3_f32 v182, v182, s4, v236
	v_exp_f32_e32 v182, v182
	v_med3_f32 v183, v183, s4, v236
	v_exp_f32_e32 v183, v183
	v_add_f32_e32 v202, v202, v76
	v_add_f32_e32 v202, v202, v77
	v_mfma_f32_32x32x16_bf16 v[34:49], v[66:69], v[134:137], v[34:49]
	v_med3_f32 v184, v184, s4, v236
	v_exp_f32_e32 v184, v184
	v_med3_f32 v185, v185, s4, v236
	v_exp_f32_e32 v185, v185
	v_add_f32_e32 v202, v202, v78
	v_add_f32_e32 v202, v202, v79
	v_mfma_f32_32x32x16_bf16 v[18:33], v[66:69], v[138:141], v[18:33]
	v_med3_f32 v186, v186, s4, v236
	v_exp_f32_e32 v186, v186
	v_med3_f32 v187, v187, s4, v236
	v_exp_f32_e32 v187, v187
	v_add_f32_e32 v202, v202, v80
	v_add_f32_e32 v202, v202, v81
	v_mfma_f32_32x32x16_bf16 v[2:17], v[66:69], v[142:145], v[2:17]
	v_med3_f32 v188, v188, s4, v236
	v_exp_f32_e32 v188, v188
	v_med3_f32 v189, v189, s4, v236
	v_exp_f32_e32 v189, v189
	v_cvt_pk_bf16_f32 v70, v74, v75
	v_cvt_pk_bf16_f32 v71, v76, v77
	v_cvt_pk_bf16_f32 v72, v78, v79
	v_cvt_pk_bf16_f32 v73, v80, v81
	ds_read_b128 v[130:133], v201 offset:24576
	ds_read_b128 v[134:137], v201 offset:28672
	ds_read_b128 v[138:141], v201 offset:32768
	ds_read_b128 v[142:145], v201 offset:36864
	s_waitcnt lgkmcnt(8)
	v_mfma_f32_32x32x16_bf16 v[50:65], v[70:73], v[146:149], v[50:65]
	v_med3_f32 v190, v190, s4, v236
	v_exp_f32_e32 v190, v190
	v_med3_f32 v191, v191, s4, v236
	v_exp_f32_e32 v191, v191
	v_add_f32_e32 v203, v182, v183
	v_add_f32_e32 v203, v203, v184
	v_mfma_f32_32x32x16_bf16 v[34:49], v[70:73], v[150:153], v[34:49]
	v_med3_f32 v192, v192, s4, v236
	v_exp_f32_e32 v192, v192
	v_med3_f32 v193, v193, s4, v236
	v_exp_f32_e32 v193, v193
	v_add_f32_e32 v203, v203, v185
	v_add_f32_e32 v203, v203, v186
	v_mfma_f32_32x32x16_bf16 v[18:33], v[70:73], v[154:157], v[18:33]
	v_med3_f32 v194, v194, s4, v236
	v_exp_f32_e32 v194, v194
	v_med3_f32 v195, v195, s4, v236
	v_exp_f32_e32 v195, v195
	v_add_f32_e32 v203, v203, v187
	v_mfma_f32_32x32x16_bf16 v[2:17], v[70:73], v[158:161], v[2:17]
	v_med3_f32 v196, v196, s4, v236
	v_exp_f32_e32 v196, v196
	v_med3_f32 v197, v197, s4, v236
	v_exp_f32_e32 v197, v197
	v_add_f32_e32 v203, v203, v188
	v_cvt_pk_bf16_f32 v182, v182, v183
	v_cvt_pk_bf16_f32 v183, v184, v185
	v_cvt_pk_bf16_f32 v184, v186, v187
	v_cvt_pk_bf16_f32 v185, v188, v189
	v_add_f32_e32 v203, v203, v189
	s_setprio 0
	s_waitcnt lgkmcnt(4)
	v_mfma_f32_32x32x16_bf16 v[50:65], v[182:185], v[162:165], v[50:65]
	v_mad_u64_u32 v[204:205], s[10:11], s86, v228, v[174:175]
	s_mul_i32 s10, s7, 0xa000
	s_add_i32 s10, s0, s10
	s_mov_b32 m0, s10
	v_lshl_add_u64 v[206:207], v[204:205], 0, s[94:95]
	global_load_lds_dwordx4 v[204:205], off
	v_add_f32_e32 v203, v203, v190
	v_add_f32_e32 v203, v203, v191
	v_add_f32_e32 v203, v203, v192
	v_mfma_f32_32x32x16_bf16 v[34:49], v[182:185], v[166:169], v[34:49]
	s_add_i32 m0, s10, 0x2000
	v_lshl_add_u64 v[204:205], v[204:205], 0, s[96:97]
	global_load_lds_dwordx4 v[206:207], off
	v_add_f32_e32 v203, v203, v193
	v_add_f32_e32 v203, v203, v194
	v_add_f32_e32 v203, v203, v195
	v_mfma_f32_32x32x16_bf16 v[18:33], v[182:185], v[170:173], v[18:33]
	s_add_i32 m0, s10, 0x4000
	s_nop 0
	global_load_lds_dwordx4 v[204:205], off
	v_lshl_add_u64 v[204:205], s[86:87], 1, v[180:181]
	s_add_i32 m0, s10, 0x6000
	v_add_f32_e32 v203, v203, v196
	v_add_f32_e32 v203, v203, v197
	v_cvt_pk_bf16_f32 v186, v190, v191
	v_cvt_pk_bf16_f32 v187, v192, v193
	v_cvt_pk_bf16_f32 v188, v194, v195
	v_cvt_pk_bf16_f32 v189, v196, v197
	v_mfma_f32_32x32x16_bf16 v[2:17], v[182:185], v[176:179], v[2:17]
	global_load_lds_dwordx4 v[204:205], off
	v_lshl_add_u64 v[204:205], v[204:205], 0, s[92:93]
	s_add_i32 m0, s10, 0x8000
	v_add_f32_e32 v202, v202, v203
	v_add_f32_e32 v0, v0, v202
	s_waitcnt lgkmcnt(0)
	v_mfma_f32_32x32x16_bf16 v[50:65], v[186:189], v[130:133], v[50:65]
	global_load_lds_dwordx4 v[204:205], off
	v_mfma_f32_32x32x16_bf16 v[34:49], v[186:189], v[134:137], v[34:49]
	v_mfma_f32_32x32x16_bf16 v[18:33], v[186:189], v[138:141], v[18:33]
	v_mfma_f32_32x32x16_bf16 v[2:17], v[186:189], v[142:145], v[2:17]
	s_waitcnt vmcnt(5) lgkmcnt(0)
	s_branch .LBB0_573
.Lat2_young:
	s_setprio 3
	v_add_u32_e32 v198, s100, v218
	v_add_u32_e32 v199, s100, v219
	v_add_u32_e32 v200, s100, v209
	v_add_u32_e32 v201, s100, v208
	ds_read_b128 v[130:133], v198 offset:0
	ds_read_b128 v[134:137], v199 offset:0
	ds_read_b128 v[138:141], v200 offset:0
	ds_read_b128 v[142:145], v201 offset:0
	ds_read_b128 v[146:149], v198 offset:8192
	ds_read_b128 v[150:153], v199 offset:8192
	ds_read_b128 v[154:157], v200 offset:8192
	ds_read_b128 v[158:161], v201 offset:8192
	ds_read_b128 v[162:165], v198 offset:16384
	ds_read_b128 v[166:169], v199 offset:16384
	ds_read_b128 v[170:173], v200 offset:16384
	ds_read_b128 v[176:179], v201 offset:16384
	s_waitcnt lgkmcnt(8)
	v_mfma_f32_32x32x16_bf16 v[66:81], v[130:133], v[118:121], 0
	v_mfma_f32_32x32x16_bf16 v[66:81], v[134:137], v[114:117], v[66:81]
	v_mfma_f32_32x32x16_bf16 v[66:81], v[138:141], v[110:113], v[66:81]
	v_mfma_f32_32x32x16_bf16 v[66:81], v[142:145], v[106:109], v[66:81]
	ds_read_b128 v[130:133], v198 offset:4096
	ds_read_b128 v[134:137], v199 offset:4096
	ds_read_b128 v[138:141], v200 offset:4096
	ds_read_b128 v[142:145], v201 offset:4096
	s_waitcnt lgkmcnt(8)
	v_mfma_f32_32x32x16_bf16 v[66:81], v[146:149], v[102:105], v[66:81]
	v_mfma_f32_32x32x16_bf16 v[66:81], v[150:153], v[98:101], v[66:81]
	v_mfma_f32_32x32x16_bf16 v[66:81], v[154:157], v[94:97], v[66:81]
	v_mfma_f32_32x32x16_bf16 v[66:81], v[158:161], v[90:93], v[66:81]
	ds_read_b128 v[146:149], v198 offset:12288
	ds_read_b128 v[150:153], v199 offset:12288
	ds_read_b128 v[154:157], v200 offset:12288
	ds_read_b128 v[158:161], v201 offset:12288
	s_waitcnt lgkmcnt(8)
	v_mfma_f32_32x32x16_bf16 v[66:81], v[162:165], v[86:89], v[66:81]
	v_mfma_f32_32x32x16_bf16 v[66:81], v[166:169], v[126:129], v[66:81]
	v_mfma_f32_32x32x16_bf16 v[66:81], v[170:173], v[82:85], v[66:81]
	v_mfma_f32_32x32x16_bf16 v[66:81], v[176:179], v[122:125], v[66:81]
	s_setprio 3
	ds_read_b128 v[162:165], v198 offset:20480
	ds_read_b128 v[166:169], v199 offset:20480
	ds_read_b128 v[170:173], v200 offset:20480
	ds_read_b128 v[176:179], v201 offset:20480
	s_waitcnt lgkmcnt(8)
	v_mfma_f32_32x32x16_bf16 v[182:197], v[130:133], v[118:121], 0
	v_mfma_f32_32x32x16_bf16 v[182:197], v[134:137], v[114:117], v[182:197]
	v_mfma_f32_32x32x16_bf16 v[182:197], v[138:141], v[110:113], v[182:197]
	v_mfma_f32_32x32x16_bf16 v[182:197], v[142:145], v[106:109], v[182:197]
	ds_read_b128 v[130:133], v198 offset:24576
	ds_read_b128 v[134:137], v198 offset:28672
	ds_read_b128 v[138:141], v198 offset:32768
	ds_read_b128 v[142:145], v198 offset:36864
	s_waitcnt lgkmcnt(8)
	v_mfma_f32_32x32x16_bf16 v[182:197], v[146:149], v[102:105], v[182:197]
	v_med3_f32 v66, v66, s4, v236
	v_exp_f32_e32 v66, v66
	v_med3_f32 v67, v67, s4, v236
	v_exp_f32_e32 v67, v67
	v_mfma_f32_32x32x16_bf16 v[182:197], v[150:153], v[98:101], v[182:197]
	v_med3_f32 v68, v68, s4, v236
	v_exp_f32_e32 v68, v68
	v_med3_f32 v69, v69, s4, v236
	v_exp_f32_e32 v69, v69
	v_mfma_f32_32x32x16_bf16 v[182:197], v[154:157], v[94:97], v[182:197]
	v_med3_f32 v70, v70, s4, v236
	v_exp_f32_e32 v70, v70
	v_med3_f32 v71, v71, s4, v236
	v_exp_f32_e32 v71, v71
	v_mfma_f32_32x32x16_bf16 v[182:197], v[158:161], v[90:93], v[182:197]
	v_med3_f32 v72, v72, s4, v236
	v_exp_f32_e32 v72, v72
	v_med3_f32 v73, v73, s4, v236
	v_exp_f32_e32 v73, v73
	ds_read_b128 v[146:149], v199 offset:24576
	ds_read_b128 v[150:153], v199 offset:28672
	ds_read_b128 v[154:157], v199 offset:32768
	ds_read_b128 v[158:161], v199 offset:36864
	s_waitcnt lgkmcnt(8)
	v_mfma_f32_32x32x16_bf16 v[182:197], v[162:165], v[86:89], v[182:197]
	v_med3_f32 v74, v74, s4, v236
	v_exp_f32_e32 v74, v74
	v_med3_f32 v75, v75, s4, v236
	v_exp_f32_e32 v75, v75
	v_add_f32_e32 v202, v66, v67
	v_add_f32_e32 v202, v202, v68
	v_mfma_f32_32x32x16_bf16 v[182:197], v[166:169], v[126:129], v[182:197]
	v_med3_f32 v76, v76, s4, v236
	v_exp_f32_e32 v76, v76
	v_med3_f32 v77, v77, s4, v236
	v_exp_f32_e32 v77, v77
	v_add_f32_e32 v202, v202, v69
	v_add_f32_e32 v202, v202, v70
	v_mfma_f32_32x32x16_bf16 v[182:197], v[170:173], v[82:85], v[182:197]
	v_med3_f32 v78, v78, s4, v236
	v_exp_f32_e32 v78, v78
	v_med3_f32 v79, v79, s4, v236
	v_exp_f32_e32 v79, v79
	v_add_f32_e32 v202, v202, v71
	v_add_f32_e32 v202, v202, v72
	v_mfma_f32_32x32x16_bf16 v[182:197], v[176:179], v[122:125], v[182:197]
	v_med3_f32 v80, v80, s4, v236
	v_exp_f32_e32 v80, v80
	v_med3_f32 v81, v81, s4, v236
	v_exp_f32_e32 v81, v81
	v_add_f32_e32 v202, v202, v73
	s_setprio 2
	ds_read_b128 v[162:165], v200 offset:24576
	ds_read_b128 v[166:169], v200 offset:28672
	ds_read_b128 v[170:173], v200 offset:32768
	ds_read_b128 v[176:179], v200 offset:36864
	v_cvt_pk_bf16_f32 v66, v66, v67
	v_cvt_pk_bf16_f32 v67, v68, v69
	v_cvt_pk_bf16_f32 v68, v70, v71
	v_cvt_pk_bf16_f32 v69, v72, v73
	v_add_f32_e32 v202, v202, v74
	v_add_f32_e32 v202, v202, v75
	s_waitcnt lgkmcnt(8)
	v_mfma_f32_32x32x16_bf16 v[50:65], v[66:69], v[130:133], v[50:65]
	v_med3_f32 v182, v182, s4, v236
	v_exp_f32_e32 v182, v182
	v_med3_f32 v183, v183, s4, v236
	v_exp_f32_e32 v183, v183
	v_add_f32_e32 v202, v202, v76
	v_add_f32_e32 v202, v202, v77
	v_mfma_f32_32x32x16_bf16 v[34:49], v[66:69], v[134:137], v[34:49]
	v_med3_f32 v184, v184, s4, v236
	v_exp_f32_e32 v184, v184
	v_med3_f32 v185, v185, s4, v236
	v_exp_f32_e32 v185, v185
	v_add_f32_e32 v202, v202, v78
	v_add_f32_e32 v202, v202, v79
	v_mfma_f32_32x32x16_bf16 v[18:33], v[66:69], v[138:141], v[18:33]
	v_med3_f32 v186, v186, s4, v236
	v_exp_f32_e32 v186, v186
	v_med3_f32 v187, v187, s4, v236
	v_exp_f32_e32 v187, v187
	v_add_f32_e32 v202, v202, v80
	v_add_f32_e32 v202, v202, v81
	v_mfma_f32_32x32x16_bf16 v[2:17], v[66:69], v[142:145], v[2:17]
	v_med3_f32 v188, v188, s4, v236
	v_exp_f32_e32 v188, v188
	v_med3_f32 v189, v189, s4, v236
	v_exp_f32_e32 v189, v189
	v_cvt_pk_bf16_f32 v70, v74, v75
	v_cvt_pk_bf16_f32 v71, v76, v77
	v_cvt_pk_bf16_f32 v72, v78, v79
	v_cvt_pk_bf16_f32 v73, v80, v81
	ds_read_b128 v[130:133], v201 offset:24576
	ds_read_b128 v[134:137], v201 offset:28672
	ds_read_b128 v[138:141], v201 offset:32768
	ds_read_b128 v[142:145], v201 offset:36864
	s_waitcnt lgkmcnt(8)
	v_mfma_f32_32x32x16_bf16 v[50:65], v[70:73], v[146:149], v[50:65]
	v_med3_f32 v190, v190, s4, v236
	v_exp_f32_e32 v190, v190
	v_med3_f32 v191, v191, s4, v236
	v_exp_f32_e32 v191, v191
	v_add_f32_e32 v203, v182, v183
	v_add_f32_e32 v203, v203, v184
	v_mfma_f32_32x32x16_bf16 v[34:49], v[70:73], v[150:153], v[34:49]
	v_med3_f32 v192, v192, s4, v236
	v_exp_f32_e32 v192, v192
	v_med3_f32 v193, v193, s4, v236
	v_exp_f32_e32 v193, v193
	v_add_f32_e32 v203, v203, v185
	v_add_f32_e32 v203, v203, v186
	v_mfma_f32_32x32x16_bf16 v[18:33], v[70:73], v[154:157], v[18:33]
	v_med3_f32 v194, v194, s4, v236
	v_exp_f32_e32 v194, v194
	v_med3_f32 v195, v195, s4, v236
	v_exp_f32_e32 v195, v195
	v_add_f32_e32 v203, v203, v187
	v_mfma_f32_32x32x16_bf16 v[2:17], v[70:73], v[158:161], v[2:17]
	v_med3_f32 v196, v196, s4, v236
	v_exp_f32_e32 v196, v196
	v_med3_f32 v197, v197, s4, v236
	v_exp_f32_e32 v197, v197
	v_add_f32_e32 v203, v203, v188
	v_cvt_pk_bf16_f32 v182, v182, v183
	v_cvt_pk_bf16_f32 v183, v184, v185
	v_cvt_pk_bf16_f32 v184, v186, v187
	v_cvt_pk_bf16_f32 v185, v188, v189
	v_add_f32_e32 v203, v203, v189
	s_setprio 1
	s_waitcnt lgkmcnt(4)
	v_mfma_f32_32x32x16_bf16 v[50:65], v[182:185], v[162:165], v[50:65]
	v_mad_u64_u32 v[204:205], s[10:11], s86, v228, v[174:175]
	s_mul_i32 s10, s7, 0xa000
	s_add_i32 s10, s0, s10
	s_mov_b32 m0, s10
	v_lshl_add_u64 v[206:207], v[204:205], 0, s[94:95]
	global_load_lds_dwordx4 v[204:205], off
	v_add_f32_e32 v203, v203, v190
	v_add_f32_e32 v203, v203, v191
	v_add_f32_e32 v203, v203, v192
	v_mfma_f32_32x32x16_bf16 v[34:49], v[182:185], v[166:169], v[34:49]
	s_add_i32 m0, s10, 0x2000
	v_lshl_add_u64 v[204:205], v[204:205], 0, s[96:97]
	global_load_lds_dwordx4 v[206:207], off
	v_add_f32_e32 v203, v203, v193
	v_add_f32_e32 v203, v203, v194
	v_add_f32_e32 v203, v203, v195
	v_mfma_f32_32x32x16_bf16 v[18:33], v[182:185], v[170:173], v[18:33]
	s_add_i32 m0, s10, 0x4000
	s_nop 0
	global_load_lds_dwordx4 v[204:205], off
	v_lshl_add_u64 v[204:205], s[86:87], 1, v[180:181]
	s_add_i32 m0, s10, 0x6000
	v_add_f32_e32 v203, v203, v196
	v_add_f32_e32 v203, v203, v197
	v_cvt_pk_bf16_f32 v186, v190, v191
	v_cvt_pk_bf16_f32 v187, v192, v193
	v_cvt_pk_bf16_f32 v188, v194, v195
	v_cvt_pk_bf16_f32 v189, v196, v197
	v_mfma_f32_32x32x16_bf16 v[2:17], v[182:185], v[176:179], v[2:17]
	global_load_lds_dwordx4 v[204:205], off
	v_lshl_add_u64 v[204:205], v[204:205], 0, s[92:93]
	s_add_i32 m0, s10, 0x8000
	v_add_f32_e32 v202, v202, v203
	v_add_f32_e32 v0, v0, v202
	s_waitcnt lgkmcnt(0)
	v_mfma_f32_32x32x16_bf16 v[50:65], v[186:189], v[130:133], v[50:65]
	global_load_lds_dwordx4 v[204:205], off
	v_mfma_f32_32x32x16_bf16 v[34:49], v[186:189], v[134:137], v[34:49]
	v_mfma_f32_32x32x16_bf16 v[18:33], v[186:189], v[138:141], v[18:33]
	v_mfma_f32_32x32x16_bf16 v[2:17], v[186:189], v[142:145], v[2:17]
	s_setprio 0
	s_waitcnt vmcnt(5) lgkmcnt(0)
	s_branch .LBB0_573
